# shift 12k MoE weight-conversion items from exposed top-k phases into in-/out-projection GEMM idle tails (queue constants only)
# speedup vs baseline: 1.0005x; 1.0005x over previous
.LBB0_279:
	s_add_u32 s66, s52, 0x8b00000
	s_addc_u32 s67, s53, 0
	s_add_u32 s82, s52, 0x15700000
	s_addc_u32 s83, s53, 0
	s_add_u32 s48, s52, 0x22300000
	s_addc_u32 s5, s53, 0
	s_add_u32 s44, s52, 0x26700000
	s_addc_u32 s71, s53, 0
	v_writelane_b32 v255, s57, 10
	s_mov_b32 s4, s48
	s_add_u32 s68, s52, 0x2ef00000
	v_writelane_b32 v255, s4, 11
	s_addc_u32 s69, s53, 0
	s_mov_b32 s70, s44
	v_writelane_b32 v255, s5, 12
	s_add_u32 s4, s52, 0x400000
	s_addc_u32 s5, s53, 0
	v_writelane_b32 v255, s4, 13
	s_nop 1
	v_writelane_b32 v255, s5, 14
	s_add_u32 s4, s52, 0x600000
	s_addc_u32 s5, s53, 0
	s_add_u32 s74, s52, 0x700000
	s_addc_u32 s75, s53, 0
	s_add_u32 s62, s52, 0x780000
	s_addc_u32 s63, s53, 0
	s_add_u32 s64, s52, 0x800000
	v_writelane_b32 v255, s4, 15
	s_addc_u32 s65, s53, 0
	s_cmp_lt_i32 s61, 3
	v_writelane_b32 v255, s5, 16
	s_cbranch_scc1 .LBB0_1001
	s_cmp_gt_i32 s60, 2
	s_cbranch_scc1 .LBB0_353
	s_cmpk_lg_i32 s56, 0x100
	s_cselect_b64 s[4:5], -1, 0
	s_cmpk_lt_i32 s2, 0x60
	s_cselect_b64 s[6:7], -1, 0
	s_or_b64 s[4:5], s[6:7], s[4:5]
	s_and_b64 vcc, exec, s[4:5]
	s_cbranch_vccnz .LBB0_285
	s_add_i32 s4, s54, 0x1d00
	s_cmpk_gt_i32 s4, 0x3fff
	s_cbranch_scc1 .LBB0_285
	v_readlane_b32 s5, v255, 6
	s_add_u32 s3, s52, 0x2b00000
	s_mulk_i32 s5, 0x2200
	s_addc_u32 s6, s53, 0
	s_add_i32 s8, s5, 0
	v_and_b32_e32 v1, 63, v0
	s_mov_b32 s7, 0x10000
	s_add_i32 s8, s8, 0x10000
	s_add_i32 s9, s54, 0x1800
	s_lshl_b32 s10, s4, 1
	s_lshl_b32 s11, s4, 5
	s_movk_i32 s12, 0xc8
	v_mov_b32_e32 v3, 0
	s_movk_i32 s13, 0x2000
	s_movk_i32 s14, 0x4000
	s_movk_i32 s15, 0x6000
	s_mov_b32 s16, 0x8000
	s_mov_b32 s17, 0xa000
	s_mov_b32 s18, 0xc000
	s_mov_b32 s19, 0xe000
	s_mov_b32 s20, 0x12000
	s_mov_b32 s21, 0x14000
	s_mov_b32 s22, 0x16000
	s_mov_b32 s23, 0x18000
	s_mov_b32 s24, 0x1a000
	s_mov_b32 s25, 0x1c000
	s_mov_b32 s26, 0x1e000
	s_mov_b32 s27, 0x20000
	s_mov_b32 s28, 0x22000
	s_mov_b32 s29, 0x24000
	s_mov_b32 s30, 0x26000
	s_mov_b32 s31, 0x28000
	s_mov_b32 s34, 0x2a000
	s_mov_b32 s35, 0x2c000
	s_mov_b32 s36, 0x2e000
	s_mov_b32 s37, 0x30000
	s_mov_b32 s38, 0x32000
	s_mov_b32 s39, 0x34000
	s_mov_b32 s41, 0x36000
	s_mov_b32 s42, 0x38000
	s_mov_b32 s43, 0x3a000
	s_mov_b32 s45, 0x3c000
	s_mov_b32 s46, 0x3e000
	s_movk_i32 s47, 0x84
.LBB0_284:
	s_addk_i32 s9, 0x500
	s_and_b32 s4, s11, 0x3e0
	s_ashr_i32 s50, s9, 10
	s_bfe_u32 s5, s9, 0x10009
	s_cmp_eq_u32 s5, 0
	s_cselect_b32 s33, s12, 0xd0
	s_add_u32 s58, s0, s33
	s_addc_u32 s59, s1, 0
	s_load_dwordx2 s[58:59], s[58:59], 0x0
	s_ashr_i32 s51, s50, 31
	s_lshl_b64 s[72:73], s[50:51], 22
	v_mov_b32_e32 v2, v1
	s_waitcnt lgkmcnt(0)
	s_add_u32 s33, s58, s72
	s_addc_u32 s49, s59, s73
	s_lshl_b64 s[50:51], s[50:51], 21
	s_add_u32 s50, s3, s50
	s_addc_u32 s51, s6, s51
	s_lshl_b32 s58, s11, 1
	s_lshl_b32 s5, s5, 7
	s_and_b32 s58, s58, 0x700
	s_and_b32 s59, s11, 0x60
	s_or_b32 s5, s58, s5
	v_ashrrev_i32_e32 v12, 5, v2
	v_lshlrev_b32_e32 v13, 2, v2
	s_and_b32 s57, s10, 0x3c0
	s_lshl_b32 s4, s4, 2
	s_or_b32 s5, s5, s59
	v_ashrrev_i32_e32 v14, 3, v2
	v_lshlrev_b32_e32 v17, 3, v2
	v_and_b32_e32 v2, 0x7c, v13
	v_mul_lo_u32 v13, v12, s47
	v_add_u32_e32 v12, s57, v12
	s_add_u32 s4, s33, s4
	v_lshlrev_b32_e32 v84, 2, v14
	v_add3_u32 v85, s8, v2, v13
	v_ashrrev_i32_e32 v13, 31, v12
	v_add_u32_e32 v14, s5, v14
	s_addc_u32 s5, s49, 0
	v_lshlrev_b64 v[12:13], 12, v[12:13]
	v_lshl_add_u64 v[22:23], s[4:5], 0, v[2:3]
	v_lshl_add_u64 v[12:13], v[22:23], 0, v[12:13]
	v_add_co_u32_e32 v22, vcc, s13, v12
	v_add_u32_e32 v86, 0x400, v85
	s_nop 0
	v_addc_co_u32_e32 v23, vcc, 0, v13, vcc
	v_add_co_u32_e32 v24, vcc, s14, v12
	v_add_u32_e32 v87, 0x800, v85
	s_nop 0
	v_addc_co_u32_e32 v25, vcc, 0, v13, vcc
	v_add_co_u32_e32 v26, vcc, s15, v12
	v_add_u32_e32 v88, 0xc00, v85
	s_nop 0
	v_addc_co_u32_e32 v27, vcc, 0, v13, vcc
	v_add_co_u32_e32 v28, vcc, s16, v12
	v_add_u32_e32 v89, 0x1000, v85
	s_nop 0
	v_addc_co_u32_e32 v29, vcc, 0, v13, vcc
	v_add_co_u32_e32 v30, vcc, s17, v12
	v_add_u32_e32 v90, 0x1400, v85
	s_nop 0
	v_addc_co_u32_e32 v31, vcc, 0, v13, vcc
	v_add_co_u32_e32 v32, vcc, s18, v12
	v_add_u32_e32 v91, 0x1800, v85
	s_nop 0
	v_addc_co_u32_e32 v33, vcc, 0, v13, vcc
	v_add_co_u32_e32 v34, vcc, s19, v12
	v_add_u32_e32 v92, 0x1c00, v85
	s_nop 0
	v_addc_co_u32_e32 v35, vcc, 0, v13, vcc
	v_add_co_u32_e32 v36, vcc, s7, v12
	v_add_u32_e32 v16, 8, v14
	s_nop 0
	v_addc_co_u32_e32 v37, vcc, 0, v13, vcc
	v_add_co_u32_e32 v38, vcc, s20, v12
	v_add_u32_e32 v18, 16, v14
	s_nop 0
	v_addc_co_u32_e32 v39, vcc, 0, v13, vcc
	v_add_co_u32_e32 v40, vcc, s21, v12
	v_add_u32_e32 v20, 24, v14
	s_nop 0
	v_addc_co_u32_e32 v41, vcc, 0, v13, vcc
	v_add_co_u32_e32 v42, vcc, s22, v12
	v_and_b32_e32 v2, 56, v17
	s_nop 0
	v_addc_co_u32_e32 v43, vcc, 0, v13, vcc
	v_add_co_u32_e32 v44, vcc, s23, v12
	s_add_u32 s4, s50, s57
	s_nop 0
	v_addc_co_u32_e32 v45, vcc, 0, v13, vcc
	v_add_co_u32_e32 v46, vcc, s24, v12
	v_ashrrev_i32_e32 v15, 31, v14
	s_nop 0
	v_addc_co_u32_e32 v47, vcc, 0, v13, vcc
	v_add_co_u32_e32 v48, vcc, s25, v12
	v_ashrrev_i32_e32 v17, 31, v16
	s_nop 0
	v_addc_co_u32_e32 v49, vcc, 0, v13, vcc
	v_add_co_u32_e32 v50, vcc, s26, v12
	v_ashrrev_i32_e32 v19, 31, v18
	s_nop 0
	v_addc_co_u32_e32 v51, vcc, 0, v13, vcc
	v_add_co_u32_e32 v52, vcc, s27, v12
	v_ashrrev_i32_e32 v21, 31, v20
	s_nop 0
	v_addc_co_u32_e32 v53, vcc, 0, v13, vcc
	v_add_co_u32_e32 v54, vcc, s28, v12
	v_mul_u32_u24_e32 v93, 0x84, v2
	s_nop 0
	v_addc_co_u32_e32 v55, vcc, 0, v13, vcc
	v_add_co_u32_e32 v56, vcc, s29, v12
	s_addc_u32 s5, s51, 0
	s_nop 0
	v_addc_co_u32_e32 v57, vcc, 0, v13, vcc
	v_add_co_u32_e32 v58, vcc, s30, v12
	v_lshlrev_b64 v[14:15], 10, v[14:15]
	s_nop 0
	v_addc_co_u32_e32 v59, vcc, 0, v13, vcc
	v_add_co_u32_e32 v60, vcc, s31, v12
	v_mov_b32_e32 v4, v3
	s_nop 0
	v_addc_co_u32_e32 v61, vcc, 0, v13, vcc
	v_add_co_u32_e32 v62, vcc, s34, v12
	v_mov_b32_e32 v5, v3
	s_nop 0
	v_addc_co_u32_e32 v63, vcc, 0, v13, vcc
	v_add_co_u32_e32 v64, vcc, s35, v12
	v_mov_b32_e32 v6, v3
	s_nop 0
	v_addc_co_u32_e32 v65, vcc, 0, v13, vcc
	v_add_co_u32_e32 v66, vcc, s36, v12
	v_mov_b32_e32 v7, v3
	s_nop 0
	v_addc_co_u32_e32 v67, vcc, 0, v13, vcc
	v_add_co_u32_e32 v68, vcc, s37, v12
	v_mov_b32_e32 v8, v3
	s_nop 0
	v_addc_co_u32_e32 v69, vcc, 0, v13, vcc
	v_add_co_u32_e32 v70, vcc, s38, v12
	v_mov_b32_e32 v9, v3
	s_nop 0
	v_addc_co_u32_e32 v71, vcc, 0, v13, vcc
	v_add_co_u32_e32 v72, vcc, s39, v12
	v_mov_b32_e32 v10, v3
	s_nop 0
	v_addc_co_u32_e32 v73, vcc, 0, v13, vcc
	v_add_co_u32_e32 v74, vcc, s41, v12
	v_mov_b32_e32 v11, v3
	s_nop 0
	v_addc_co_u32_e32 v75, vcc, 0, v13, vcc
	v_add_co_u32_e32 v76, vcc, s42, v12
	s_addk_i32 s10, 0xa00
	s_nop 0
	v_addc_co_u32_e32 v77, vcc, 0, v13, vcc
	v_add_co_u32_e32 v78, vcc, s43, v12
	s_add_i32 s11, s11, 0xa000
	s_nop 0
	v_addc_co_u32_e32 v79, vcc, 0, v13, vcc
	v_add_co_u32_e32 v80, vcc, s45, v12
	s_cmpk_lt_i32 s9, 0x3b00
	s_nop 0
	v_addc_co_u32_e32 v81, vcc, 0, v13, vcc
	v_add_co_u32_e32 v82, vcc, s46, v12
	s_nop 1
	v_addc_co_u32_e32 v83, vcc, 0, v13, vcc
	global_load_dword v94, v[12:13], off
	s_nop 0
	global_load_dword v22, v[22:23], off
	s_nop 0
	global_load_dword v23, v[24:25], off
	s_nop 0
	global_load_dword v24, v[26:27], off
	global_load_dword v25, v[28:29], off
	s_nop 0
	global_load_dword v26, v[30:31], off
	global_load_dword v27, v[32:33], off
	global_load_dword v28, v[34:35], off
	global_load_dword v29, v[36:37], off
	s_nop 0
	global_load_dword v30, v[38:39], off
	global_load_dword v31, v[40:41], off
	global_load_dword v32, v[42:43], off
	global_load_dword v33, v[44:45], off
	global_load_dword v34, v[46:47], off
	global_load_dword v35, v[48:49], off
	global_load_dword v36, v[50:51], off
	global_load_dword v37, v[52:53], off
	global_load_dword v38, v[54:55], off
	global_load_dword v39, v[56:57], off
	global_load_dword v40, v[58:59], off
	global_load_dword v41, v[60:61], off
	global_load_dword v42, v[62:63], off
	global_load_dword v43, v[64:65], off
	global_load_dword v44, v[66:67], off
	global_load_dword v45, v[68:69], off
	global_load_dword v46, v[70:71], off
	global_load_dword v47, v[72:73], off
	global_load_dword v48, v[74:75], off
	global_load_dword v49, v[76:77], off
	global_load_dword v50, v[78:79], off
	global_load_dword v51, v[80:81], off
	global_load_dword v52, v[82:83], off
	s_waitcnt vmcnt(30)
	ds_write2_b32 v85, v94, v22 offset1:66
	s_waitcnt vmcnt(28)
	ds_write2_b32 v85, v23, v24 offset0:132 offset1:198
	s_waitcnt vmcnt(26)
	ds_write2_b32 v86, v25, v26 offset0:8 offset1:74
	s_waitcnt vmcnt(24)
	ds_write2_b32 v86, v27, v28 offset0:140 offset1:206
	s_waitcnt vmcnt(22)
	ds_write2_b32 v87, v29, v30 offset0:16 offset1:82
	s_waitcnt vmcnt(20)
	ds_write2_b32 v87, v31, v32 offset0:148 offset1:214
	s_waitcnt vmcnt(18)
	ds_write2_b32 v88, v33, v34 offset0:24 offset1:90
	s_waitcnt vmcnt(16)
	ds_write2_b32 v88, v35, v36 offset0:156 offset1:222
	s_waitcnt vmcnt(14)
	ds_write2_b32 v89, v37, v38 offset0:32 offset1:98
	s_waitcnt vmcnt(12)
	ds_write2_b32 v89, v39, v40 offset0:164 offset1:230
	s_waitcnt vmcnt(10)
	ds_write2_b32 v90, v41, v42 offset0:40 offset1:106
	s_waitcnt vmcnt(8)
	ds_write2_b32 v90, v43, v44 offset0:172 offset1:238
	s_waitcnt vmcnt(6)
	ds_write2_b32 v91, v45, v46 offset0:48 offset1:114
	s_waitcnt vmcnt(4)
	ds_write2_b32 v91, v47, v48 offset0:180 offset1:246
	s_waitcnt vmcnt(2)
	ds_write2_b32 v92, v49, v50 offset0:56 offset1:122
	s_waitcnt vmcnt(0)
	ds_write2_b32 v92, v51, v52 offset0:188 offset1:254
	s_waitcnt lgkmcnt(0)
	v_lshlrev_b64 v[12:13], 10, v[16:17]
	v_lshlrev_b64 v[16:17], 10, v[18:19]
	v_lshlrev_b64 v[18:19], 10, v[20:21]
	v_lshl_add_u64 v[20:21], s[4:5], 0, v[2:3]
	v_add3_u32 v2, s8, v93, v84
	v_lshl_add_u64 v[14:15], v[20:21], 0, v[14:15]
	v_lshl_add_u64 v[12:13], v[20:21], 0, v[12:13]
	v_lshl_add_u64 v[16:17], v[20:21], 0, v[16:17]
	v_lshl_add_u64 v[18:19], v[20:21], 0, v[18:19]
	ds_read2_b32 v[20:21], v2 offset1:8
	ds_read2_b32 v[22:23], v2 offset0:33 offset1:41
	ds_read2_b32 v[24:25], v2 offset0:66 offset1:74
	ds_read2_b32 v[26:27], v2 offset0:99 offset1:107
	ds_read2_b32 v[28:29], v2 offset0:132 offset1:140
	ds_read2_b32 v[30:31], v2 offset0:165 offset1:173
	ds_read2_b32 v[32:33], v2 offset0:198 offset1:206
	ds_read2_b32 v[34:35], v2 offset0:231 offset1:239
	ds_read2_b32 v[36:37], v2 offset0:16 offset1:24
	ds_read2_b32 v[38:39], v2 offset0:49 offset1:57
	ds_read2_b32 v[40:41], v2 offset0:82 offset1:90
	ds_read2_b32 v[42:43], v2 offset0:115 offset1:123
	ds_read2_b32 v[44:45], v2 offset0:148 offset1:156
	ds_read2_b32 v[46:47], v2 offset0:181 offset1:189
	ds_read2_b32 v[48:49], v2 offset0:214 offset1:222
	ds_read2_b32 v[50:51], v2 offset0:247 offset1:255
	s_waitcnt lgkmcnt(14)
	v_mul_f32_e32 v2, 0x42000000, v20
	v_mul_f32_e32 v20, 0x42000000, v22
	s_waitcnt lgkmcnt(13)
	v_mul_f32_e32 v22, 0x42000000, v24
	s_waitcnt lgkmcnt(12)
	v_mul_f32_e32 v24, 0x42000000, v26
	s_waitcnt lgkmcnt(11)
	v_mul_f32_e32 v26, 0x42000000, v28
	s_waitcnt lgkmcnt(10)
	v_mul_f32_e32 v28, 0x42000000, v30
	v_mul_f32_e32 v21, 0x42000000, v21
	v_mul_f32_e32 v23, 0x42000000, v23
	v_mul_f32_e32 v29, 0x42000000, v29
	v_mul_f32_e32 v31, 0x42000000, v31
	v_cvt_pk_fp8_f32 v4, v2, v20
	v_cvt_pk_fp8_f32 v5, v26, v28
	s_waitcnt lgkmcnt(9)
	v_mul_f32_e32 v30, 0x42000000, v32
	s_waitcnt lgkmcnt(8)
	v_mul_f32_e32 v32, 0x42000000, v34
	v_mul_f32_e32 v34, 0x42000000, v35
	s_waitcnt lgkmcnt(7)
	v_mul_f32_e32 v35, 0x42000000, v36
	s_waitcnt lgkmcnt(6)
	v_mul_f32_e32 v36, 0x42000000, v38
	s_waitcnt lgkmcnt(5)
	v_mul_f32_e32 v38, 0x42000000, v40
	s_waitcnt lgkmcnt(4)
	v_mul_f32_e32 v40, 0x42000000, v42
	s_waitcnt lgkmcnt(3)
	v_mul_f32_e32 v42, 0x42000000, v44
	s_waitcnt lgkmcnt(2)
	v_mul_f32_e32 v44, 0x42000000, v46
	v_cvt_pk_fp8_f32 v6, v21, v23
	v_cvt_pk_fp8_f32 v7, v29, v31
	v_mul_f32_e32 v37, 0x42000000, v37
	v_mul_f32_e32 v39, 0x42000000, v39
	v_mul_f32_e32 v45, 0x42000000, v45
	v_mul_f32_e32 v47, 0x42000000, v47
	v_cvt_pk_fp8_f32 v8, v35, v36
	v_cvt_pk_fp8_f32 v9, v42, v44
	v_cvt_pk_fp8_f32 v10, v37, v39
	v_cvt_pk_fp8_f32 v11, v45, v47
	v_mul_f32_e32 v25, 0x42000000, v25
	v_mul_f32_e32 v27, 0x42000000, v27
	v_mul_f32_e32 v33, 0x42000000, v33
	v_cvt_pk_fp8_f32 v4, v22, v24 op_sel:[0,0,1]
	v_cvt_pk_fp8_f32 v5, v30, v32 op_sel:[0,0,1]
	s_waitcnt lgkmcnt(1)
	v_mul_f32_e32 v46, 0x42000000, v48
	s_waitcnt lgkmcnt(0)
	v_mul_f32_e32 v48, 0x42000000, v50
	v_cvt_pk_fp8_f32 v6, v25, v27 op_sel:[0,0,1]
	v_cvt_pk_fp8_f32 v7, v33, v34 op_sel:[0,0,1]
	v_mul_f32_e32 v41, 0x42000000, v41
	v_mul_f32_e32 v43, 0x42000000, v43
	v_mul_f32_e32 v49, 0x42000000, v49
	v_mul_f32_e32 v50, 0x42000000, v51
	v_cvt_pk_fp8_f32 v8, v38, v40 op_sel:[0,0,1]
	v_cvt_pk_fp8_f32 v9, v46, v48 op_sel:[0,0,1]
	v_cvt_pk_fp8_f32 v10, v41, v43 op_sel:[0,0,1]
	v_cvt_pk_fp8_f32 v11, v49, v50 op_sel:[0,0,1]
	global_store_dwordx2 v[14:15], v[4:5], off
	global_store_dwordx2 v[12:13], v[6:7], off
	global_store_dwordx2 v[16:17], v[8:9], off
	global_store_dwordx2 v[18:19], v[10:11], off
	s_waitcnt lgkmcnt(0)
	s_cbranch_scc1 .LBB0_284

.LBB0_696:
	s_cmpk_lt_u32 s2, 0x80
	s_cselect_b64 s[4:5], -1, 0
	s_cmpk_gt_u32 s2, 0x7f
	s_cselect_b64 s[10:11], -1, 0
	s_movk_i32 s3, 0x4000
	s_and_b64 s[6:7], s[10:11], exec
	s_cselect_b32 s12, s3, 0x6400
	s_movk_i32 s3, 0x6c00
	s_cselect_b32 s3, 0x6400, s3
	s_cmpk_eq_i32 s56, 0x100
	s_cselect_b64 s[6:7], -1, 0
	s_and_b64 s[8:9], s[6:7], exec
	s_cselect_b32 s3, s3, 0x6000
	s_cselect_b32 s18, s12, s54
	s_cmp_ge_u32 s18, s3
	s_movk_i32 s19, 0x6000
	s_waitcnt vmcnt(0)
	s_barrier
	s_cbranch_scc1 .LBB0_711
	v_readlane_b32 s8, v255, 7
	s_and_b32 s8, s8, 0x3f8
	v_readlane_b32 s13, v255, 6
	s_add_i32 s20, s13, s8
	s_lshl_b32 s21, s20, 1
	s_movk_i32 s12, 0x800
	s_and_b64 s[8:9], s[10:11], exec
	s_cselect_b32 s12, s12, 0x400
	s_and_b64 s[8:9], s[6:7], exec
	s_mul_i32 s8, s13, 0x2200
	s_cselect_b32 s22, s12, s55
	s_add_i32 s24, s8, 0
	v_cndmask_b32_e64 v2, 0, 1, s[4:5]
	v_and_b32_e32 v1, 63, v0
	s_mov_b32 s9, 0
	s_mov_b32 s23, 0x10000
	s_add_i32 s24, s24, 0x10000
	s_and_b64 s[10:11], s[10:11], s[6:7]
	v_cmp_ne_u32_e64 s[4:5], 1, v2
	v_mov_b32_e32 v3, 0
	s_movk_i32 s25, 0x2000
	s_movk_i32 s26, 0x4000
	s_mov_b32 s27, 0x8000
	s_mov_b32 s28, 0xa000
	s_mov_b32 s29, 0xc000
	s_mov_b32 s30, 0xe000
	s_mov_b32 s31, 0x12000
	s_mov_b32 s34, 0x14000
	s_mov_b32 s35, 0x16000
	s_mov_b32 s36, 0x18000
	s_mov_b32 s37, 0x1a000
	s_mov_b32 s38, 0x1c000
	s_mov_b32 s39, 0x1e000
	s_mov_b32 s41, 0x20000
	s_mov_b32 s42, 0x22000
	s_mov_b32 s43, 0x24000
	s_mov_b32 s45, 0x26000
	s_mov_b32 s46, 0x28000
	s_mov_b32 s47, 0x2a000
	s_mov_b32 s49, 0x2c000
	s_mov_b32 s50, 0x2e000
	s_mov_b32 s51, 0x30000
	s_mov_b32 s57, 0x32000
	s_mov_b32 s58, 0x34000
	s_mov_b32 s59, 0x36000
	s_mov_b32 s72, 0x38000
	s_mov_b32 s73, 0x3a000
	s_mov_b32 s78, 0x3c000
	s_mov_b32 s79, 0x3e000
	s_movk_i32 s86, 0x84
	s_branch .LBB0_699

.LBB0_1002:
	s_cmp_gt_i32 s60, 14
	s_cbranch_scc1 .LBB0_1075
	s_cmpk_lg_i32 s56, 0x100
	s_cselect_b64 s[4:5], -1, 0
	s_cmpk_lt_i32 s2, 0x60
	s_cselect_b64 s[6:7], -1, 0
	s_or_b64 s[4:5], s[6:7], s[4:5]
	s_and_b64 vcc, exec, s[4:5]
	s_cbranch_vccnz .LBB0_1011
	s_add_i32 s3, s54, 0x6900
	s_cmp_gt_i32 s3, 0x93ff
	s_cbranch_scc1 .LBB0_1011
	v_readlane_b32 s4, v255, 6
	s_mulk_i32 s4, 0x2200
	s_add_i32 s11, s4, 0
	v_and_b32_e32 v1, 63, v0
	s_mov_b32 s5, 0
	s_mov_b32 s10, 0x10000
	s_add_i32 s11, s11, 0x10000
	s_lshl_b32 s12, s3, 1
	s_lshl_b32 s13, s3, 5
	s_mov_b32 s14, 0x7b00000
	s_waitcnt vmcnt(0)
	v_mov_b32_e32 v3, 0
	s_movk_i32 s15, 0x2000
	s_movk_i32 s16, 0x4000
	s_movk_i32 s17, 0x6000
	s_mov_b32 s18, 0x8000
	s_mov_b32 s19, 0xa000
	s_mov_b32 s20, 0xc000
	s_mov_b32 s21, 0xe000
	s_mov_b32 s22, 0x12000
	s_mov_b32 s23, 0x14000
	s_mov_b32 s24, 0x16000
	s_mov_b32 s25, 0x18000
	s_mov_b32 s26, 0x1a000
	s_mov_b32 s27, 0x1c000
	s_mov_b32 s28, 0x1e000
	s_mov_b32 s29, 0x20000
	s_mov_b32 s30, 0x22000
	s_mov_b32 s31, 0x24000
	s_mov_b32 s34, 0x26000
	s_mov_b32 s35, 0x28000
	s_mov_b32 s36, 0x2a000
	s_mov_b32 s37, 0x2c000
	s_mov_b32 s38, 0x2e000
	s_mov_b32 s39, 0x30000
	s_mov_b32 s41, 0x32000
	s_mov_b32 s42, 0x34000
	s_mov_b32 s43, 0x36000
	s_mov_b32 s45, 0x38000
	s_mov_b32 s46, 0x3a000
	s_mov_b32 s47, 0x3c000
	s_mov_b32 s49, 0x3e000
	s_movk_i32 s50, 0x84
	s_mov_b32 s51, 0x4b00000
	s_movk_i32 s57, 0xc8
	s_branch .LBB0_1007
.LBB0_1006:
	s_add_i32 s4, s3, 0x500
	s_addk_i32 s12, 0xa00
	s_add_i32 s13, s13, 0xa000
	s_cmp_lt_i32 s3, 0x8f00
	s_mov_b32 s3, s4
	s_cbranch_scc0 .LBB0_1011

.LBB0_1314:
	s_cmp_gt_i32 s60, 18
	s_cselect_b64 s[4:5], -1, 0
	s_cmp_lt_i32 s61, 19
	s_cselect_b64 s[6:7], -1, 0
	s_or_b64 s[4:5], s[4:5], s[6:7]
	s_and_b64 vcc, exec, s[4:5]
	s_cbranch_vccnz .LBB0_1390
	s_cmpk_lg_i32 s56, 0x100
	s_cselect_b64 s[4:5], -1, 0
	s_cmp_lt_i32 s2, 32
	s_cselect_b64 s[6:7], -1, 0
	s_or_b64 s[4:5], s[6:7], s[4:5]
	s_and_b64 vcc, exec, s[4:5]
	s_cbranch_vccnz .LBB0_1323
	s_add_i32 s3, s54, 0x9300
	s_cmp_gt_i32 s3, 0xbfff
	s_cbranch_scc1 .LBB0_1323
	v_readlane_b32 s4, v255, 6
	s_mulk_i32 s4, 0x2200
	s_add_i32 s11, s4, 0
	v_and_b32_e32 v1, 63, v0
	s_mov_b32 s5, 0
	s_mov_b32 s10, 0x10000
	s_add_i32 s11, s11, 0x10000
	s_lshl_b32 s12, s3, 1
	s_lshl_b32 s13, s3, 5
	s_mov_b32 s14, 0x7b00000
	s_waitcnt vmcnt(0)
	v_mov_b32_e32 v3, 0
	s_movk_i32 s15, 0x2000
	s_movk_i32 s16, 0x4000
	s_movk_i32 s17, 0x6000
	s_mov_b32 s18, 0x8000
	s_mov_b32 s19, 0xa000
	s_mov_b32 s20, 0xc000
	s_mov_b32 s21, 0xe000
	s_mov_b32 s22, 0x12000
	s_mov_b32 s23, 0x14000
	s_mov_b32 s24, 0x16000
	s_mov_b32 s25, 0x18000
	s_mov_b32 s26, 0x1a000
	s_mov_b32 s27, 0x1c000
	s_mov_b32 s28, 0x1e000
	s_mov_b32 s29, 0x20000
	s_mov_b32 s30, 0x22000
	s_mov_b32 s31, 0x24000
	s_mov_b32 s34, 0x26000
	s_mov_b32 s35, 0x28000
	s_mov_b32 s36, 0x2a000
	s_mov_b32 s37, 0x2c000
	s_mov_b32 s38, 0x2e000
	s_mov_b32 s39, 0x30000
	s_mov_b32 s41, 0x32000
	s_mov_b32 s42, 0x34000
	s_mov_b32 s43, 0x36000
	s_mov_b32 s45, 0x38000
	s_mov_b32 s46, 0x3a000
	s_mov_b32 s47, 0x3c000
	s_mov_b32 s49, 0x3e000
	s_movk_i32 s50, 0x84
	s_mov_b32 s51, 0x4b00000
	s_movk_i32 s57, 0xc8
	s_branch .LBB0_1319
.LBB0_1318:
	s_add_i32 s4, s3, 0x700
	s_addk_i32 s12, 0xe00
	s_add_i32 s13, s13, 0xe000
	s_cmp_lt_i32 s3, 0xb900
	s_mov_b32 s3, s4
	s_cbranch_scc0 .LBB0_1323

.LBB0_1580:
	s_cmpk_lt_u32 s2, 0x80
	s_cselect_b64 s[4:5], -1, 0
	s_cmpk_gt_u32 s2, 0x7f
	s_cselect_b64 s[10:11], -1, 0
	s_mov_b32 s3, 0xc000
	s_and_b64 s[6:7], s[10:11], exec
	s_cselect_b32 s12, s3, 0xcc00
	s_add_i32 s13, s54, 0x6000
	s_cmpk_eq_i32 s56, 0x100
	s_cselect_b64 s[6:7], -1, 0
	s_mov_b32 s18, 0xc000
	s_and_b64 s[8:9], s[6:7], exec
	s_cselect_b32 s19, 0xcc00, s18
	s_cselect_b32 s20, s12, s13
	s_movk_i32 s3, 0x6000
	s_cmp_ge_u32 s20, s19
	s_waitcnt vmcnt(0)
	s_barrier
	s_cbranch_scc1 .LBB0_1595
	v_readlane_b32 s8, v255, 7
	s_and_b32 s8, s8, 0x3f8
	v_readlane_b32 s13, v255, 6
	s_add_i32 s21, s13, s8
	s_lshl_b32 s22, s21, 1
	s_movk_i32 s12, 0x800
	s_and_b64 s[8:9], s[10:11], exec
	s_cselect_b32 s12, s12, 0x400
	s_and_b64 s[8:9], s[6:7], exec
	s_mul_i32 s8, s13, 0x2200
	s_cselect_b32 s23, s12, s55
	s_add_i32 s25, s8, 0
	v_cndmask_b32_e64 v2, 0, 1, s[4:5]
	v_and_b32_e32 v1, 63, v0
	s_mov_b32 s9, 0
	s_mov_b32 s24, 0x10000
	s_add_i32 s25, s25, 0x10000
	s_and_b64 s[10:11], s[10:11], s[6:7]
	v_cmp_ne_u32_e64 s[4:5], 1, v2
	v_mov_b32_e32 v3, 0
	s_movk_i32 s26, 0x2000
	s_movk_i32 s27, 0x4000
	s_mov_b32 s28, 0x8000
	s_mov_b32 s29, 0xa000
	s_mov_b32 s30, 0xe000
	s_mov_b32 s31, 0x12000
	s_mov_b32 s34, 0x14000
	s_mov_b32 s35, 0x16000
	s_mov_b32 s36, 0x18000
	s_mov_b32 s37, 0x1a000
	s_mov_b32 s38, 0x1c000
	s_mov_b32 s39, 0x1e000
	s_mov_b32 s41, 0x20000
	s_mov_b32 s42, 0x22000
	s_mov_b32 s43, 0x24000
	s_mov_b32 s45, 0x26000
	s_mov_b32 s46, 0x28000
	s_mov_b32 s47, 0x2a000
	s_mov_b32 s49, 0x2c000
	s_mov_b32 s57, 0x2e000
	s_mov_b32 s58, 0x30000
	s_mov_b32 s59, 0x32000
	s_mov_b32 s72, 0x34000
	s_mov_b32 s73, 0x36000
	s_mov_b32 s78, 0x38000
	s_mov_b32 s79, 0x3a000
	s_mov_b32 s84, 0x3c000
	s_mov_b32 s85, 0x3e000
	s_movk_i32 s86, 0x84
	s_branch .LBB0_1583

.LBB0_1885:
	s_cmp_lt_i32 s61, 27
	s_cbranch_scc1 .LBB0_2670
	s_cmp_gt_i32 s60, 26
	s_cbranch_scc1 .LBB0_1959
	s_cmpk_lg_i32 s56, 0x100
	s_cselect_b64 s[4:5], -1, 0
	s_cmp_lt_i32 s2, 48
	s_cselect_b64 s[6:7], -1, 0
	s_or_b64 s[4:5], s[6:7], s[4:5]
	s_and_b64 vcc, exec, s[4:5]
	s_cbranch_vccnz .LBB0_1895
	s_add_i32 s3, s54, 0xca80
	s_cmp_gt_i32 s3, 0x10cff
	s_cbranch_scc1 .LBB0_1895
	v_readlane_b32 s4, v255, 6
	s_mulk_i32 s4, 0x2200
	s_add_i32 s11, s4, 0
	v_and_b32_e32 v1, 63, v0
	s_mov_b32 s5, 0
	s_mov_b32 s10, 0x10000
	s_add_i32 s11, s11, 0x10000
	s_lshl_b32 s12, s3, 1
	s_lshl_b32 s13, s3, 5
	s_waitcnt vmcnt(0)
	v_mov_b32_e32 v3, 0
	s_movk_i32 s14, 0x2000
	s_movk_i32 s15, 0x4000
	s_movk_i32 s16, 0x6000
	s_mov_b32 s17, 0x8000
	s_mov_b32 s18, 0xa000
	s_mov_b32 s19, 0xc000
	s_mov_b32 s20, 0xe000
	s_mov_b32 s21, 0x12000
	s_mov_b32 s22, 0x14000
	s_mov_b32 s23, 0x16000
	s_mov_b32 s24, 0x18000
	s_mov_b32 s25, 0x1a000
	s_mov_b32 s26, 0x1c000
	s_mov_b32 s27, 0x1e000
	s_mov_b32 s28, 0x20000
	s_mov_b32 s29, 0x22000
	s_mov_b32 s30, 0x24000
	s_mov_b32 s31, 0x26000
	s_mov_b32 s34, 0x28000
	s_mov_b32 s35, 0x2a000
	s_mov_b32 s36, 0x2c000
	s_mov_b32 s37, 0x2e000
	s_mov_b32 s38, 0x30000
	s_mov_b32 s39, 0x32000
	s_mov_b32 s41, 0x34000
	s_mov_b32 s42, 0x36000
	s_mov_b32 s43, 0x38000
	s_mov_b32 s45, 0x3a000
	s_mov_b32 s46, 0x3c000
	s_mov_b32 s47, 0x3e000
	s_movk_i32 s49, 0x84
	s_movk_i32 s50, 0xc8
	s_branch .LBB0_1891
.LBB0_1890:
	s_add_i32 s4, s3, 0x680
	s_addk_i32 s12, 0xd00
	s_add_i32 s13, s13, 0xd000
	s_cmp_lt_i32 s3, 0x10680
	s_mov_b32 s3, s4
	s_cbranch_scc0 .LBB0_1895

.LBB0_2349:
	s_cmpk_lt_u32 s2, 0x80
	s_cselect_b64 s[4:5], -1, 0
	s_cmpk_gt_u32 s2, 0x7f
	s_cselect_b64 s[10:11], -1, 0
	s_mov_b32 s3, 0x10d00
	s_and_b64 s[6:7], s[10:11], exec
	s_cselect_b32 s12, s3, 0x12980
	s_mov_b32 s3, 0x13900
	s_cselect_b32 s13, 0x12980, s3
	s_add_i32 s14, s54, 0xc000
	s_cmpk_eq_i32 s56, 0x100
	s_cselect_b64 s[6:7], -1, 0
	s_and_b64 s[8:9], s[6:7], exec
	s_cselect_b32 s18, s13, 0x12000
	s_cselect_b32 s19, s12, s14
	s_mov_b32 s3, 0xc000
	s_cmp_ge_u32 s19, s18
	s_mov_b32 s20, 0x12000
	s_waitcnt vmcnt(0)
	s_barrier
	s_cbranch_scc1 .LBB0_2364
	v_readlane_b32 s8, v255, 7
	s_and_b32 s8, s8, 0x3f8
	v_readlane_b32 s13, v255, 6
	s_add_i32 s21, s13, s8
	s_lshl_b32 s22, s21, 1
	s_movk_i32 s12, 0x800
	s_and_b64 s[8:9], s[10:11], exec
	s_cselect_b32 s12, s12, 0x400
	s_and_b64 s[8:9], s[6:7], exec
	s_mul_i32 s8, s13, 0x2200
	s_cselect_b32 s23, s12, s55
	s_add_i32 s25, s8, 0
	v_cndmask_b32_e64 v2, 0, 1, s[4:5]
	v_and_b32_e32 v1, 63, v0
	s_mov_b32 s9, 0
	s_mov_b32 s24, 0x10000
	s_add_i32 s25, s25, 0x10000
	s_and_b64 s[10:11], s[10:11], s[6:7]
	v_cmp_ne_u32_e64 s[4:5], 1, v2
	v_mov_b32_e32 v3, 0
	s_movk_i32 s26, 0x2000
	s_movk_i32 s27, 0x4000
	s_movk_i32 s28, 0x6000
	s_mov_b32 s29, 0x8000
	s_mov_b32 s30, 0xa000
	s_mov_b32 s31, 0xe000
	s_mov_b32 s34, 0x14000
	s_mov_b32 s35, 0x16000
	s_mov_b32 s36, 0x18000
	s_mov_b32 s37, 0x1a000
	s_mov_b32 s38, 0x1c000
	s_mov_b32 s39, 0x1e000
	s_mov_b32 s41, 0x20000
	s_mov_b32 s42, 0x22000
	s_mov_b32 s43, 0x24000
	s_mov_b32 s45, 0x26000
	s_mov_b32 s46, 0x28000
	s_mov_b32 s47, 0x2a000
	s_mov_b32 s49, 0x2c000
	s_mov_b32 s57, 0x2e000
	s_mov_b32 s58, 0x30000
	s_mov_b32 s59, 0x32000
	s_mov_b32 s72, 0x34000
	s_mov_b32 s73, 0x36000
	s_mov_b32 s78, 0x38000
	s_mov_b32 s79, 0x3a000
	s_mov_b32 s84, 0x3c000
	s_mov_b32 s85, 0x3e000
	s_movk_i32 s86, 0x84
	s_branch .LBB0_2352
